# VT: fold two dead v_mov copies in the unmasked attention tile (on VH2)
# baseline (speedup 1.0000x reference)
.LBB0_651:
	s_max_i32 s0, s14, 0
	s_mov_b32 s6, s14
	s_add_i32 s14, s0, -1
	s_lshl_b32 s0, s14, 5
	s_add_i32 s0, s23, s0
	s_cmp_gt_i32 s6, 0
	s_waitcnt vmcnt(0)
	s_cselect_b32 s0, s0, 0x8002
	s_waitcnt lgkmcnt(0)
	v_or_b32_e32 v2, s0, v135
	v_ashrrev_i32_e32 v3, 31, v2
	v_lshlrev_b64 v[2:3], 11, v[2:3]
	ds_write_b128 v167, v[108:111]
	ds_write_b128 v167, v[104:107] offset:144
	ds_write_b128 v167, v[100:103] offset:288
	ds_write_b128 v167, v[96:99] offset:432
	ds_write_b128 v168, v[92:95] offset:4608
	ds_write_b128 v168, v[88:91] offset:4800
	ds_write_b128 v168, v[84:87] offset:4992
	ds_write_b128 v168, v[80:83] offset:5184
	v_lshl_or_b32 v2, v158, 1, v2
	v_lshl_add_u64 v[4:5], s[24:25], 0, v[2:3]
	v_lshl_add_u64 v[2:3], s[26:27], 0, v[2:3]
	global_load_dwordx4 v[108:111], v[4:5], off offset:-4096
	global_load_dwordx4 v[104:107], v[4:5], off offset:-2048
	global_load_dwordx4 v[100:103], v[4:5], off
	global_load_dwordx4 v[96:99], v[4:5], off offset:2048
	global_load_dwordx4 v[92:95], v[2:3], off offset:-4096
	global_load_dwordx4 v[88:91], v[2:3], off offset:-2048
	global_load_dwordx4 v[84:87], v[2:3], off
	global_load_dwordx4 v[80:83], v[2:3], off offset:2048
	ds_read_b128 v[128:131], v169
	ds_read_b128 v[10:13], v169 offset:32
	ds_read_b128 v[6:9], v169 offset:64
	ds_read_b128 v[2:5], v169 offset:96
	s_cmp_lt_i32 s6, 0
	s_cselect_b64 s[0:1], -1, 0
	s_cmp_gt_i32 s6, -1
	s_cselect_b64 s[2:3], -1, 0
	s_cmp_lg_u32 s6, s22
	s_cselect_b64 s[6:7], -1, 0
	s_and_b64 s[6:7], s[2:3], s[6:7]
	s_mov_b64 s[18:19], -1
	s_and_b64 vcc, exec, s[6:7]
	v_mbcnt_hi_u32_b32 v1, -1, v195
	s_mov_b64 s[6:7], -1
	s_cbranch_vccz .LBB0_653
	s_waitcnt lgkmcnt(3)
	v_mfma_f32_32x32x16_bf16 v[48:63], v[128:131], v[112:115], 0
	s_mov_b64 s[6:7], 0
	s_waitcnt lgkmcnt(2)
	v_mfma_f32_32x32x16_bf16 v[48:63], v[10:13], v[116:119], v[48:63]
	s_waitcnt lgkmcnt(1)
	v_mfma_f32_32x32x16_bf16 v[48:63], v[6:9], v[120:123], v[48:63]
	s_waitcnt lgkmcnt(0)
	v_mfma_f32_32x32x16_bf16 v[48:63], v[2:5], v[124:127], v[48:63]
	ds_read_b64_tr_b16 v[244:245], v141
	ds_read_b64_tr_b16 v[246:247], v141 offset:1536
	ds_read_b64_tr_b16 v[188:189], v141 offset:3072
	ds_read_b64_tr_b16 v[190:191], v141 offset:4608
	ds_read_b64_tr_b16 v[196:197], v141 offset:64
	ds_read_b64_tr_b16 v[198:199], v141 offset:1600
	ds_read_b64_tr_b16 v[184:185], v141 offset:3136
	ds_read_b64_tr_b16 v[186:187], v141 offset:4672
	s_nop 11
	v_exp_f32_e32 v14, v48
	v_exp_f32_e32 v15, v49
	v_exp_f32_e32 v48, v50
	v_exp_f32_e32 v49, v51
	v_exp_f32_e32 v50, v52
	v_exp_f32_e32 v51, v53
	v_exp_f32_e32 v52, v54
	v_exp_f32_e32 v53, v55
	v_exp_f32_e32 v54, v56
	v_exp_f32_e32 v55, v57
	v_exp_f32_e32 v56, v58
	v_exp_f32_e32 v57, v59
	v_exp_f32_e32 v58, v60
	v_exp_f32_e32 v59, v61
	v_exp_f32_e32 v60, v62
	v_exp_f32_e32 v61, v63
	v_pk_add_f32 v[14:15], v[14:15], 1.0 op_sel_hi:[1,0]
	v_pk_add_f32 v[48:49], v[48:49], 1.0 op_sel_hi:[1,0]
	v_pk_add_f32 v[58:59], v[58:59], 1.0 op_sel_hi:[1,0]
	v_pk_add_f32 v[50:51], v[50:51], 1.0 op_sel_hi:[1,0]
	v_pk_add_f32 v[52:53], v[52:53], 1.0 op_sel_hi:[1,0]
	v_rcp_f32_e32 v14, v14
	v_rcp_f32_e32 v15, v15
	v_rcp_f32_e32 v48, v48
	v_rcp_f32_e32 v49, v49
	v_rcp_f32_e32 v192, v58
	v_rcp_f32_e32 v193, v59
	v_pk_add_f32 v[58:59], v[60:61], 1.0 op_sel_hi:[1,0]
	v_pk_add_f32 v[54:55], v[54:55], 1.0 op_sel_hi:[1,0]
	v_pk_add_f32 v[56:57], v[56:57], 1.0 op_sel_hi:[1,0]
	v_rcp_f32_e32 v50, v50
	v_rcp_f32_e32 v51, v51
	v_rcp_f32_e32 v52, v52
	v_rcp_f32_e32 v53, v53
	v_rcp_f32_e32 v205, v59
	v_rcp_f32_e32 v68, v54
	v_rcp_f32_e32 v69, v55
	v_rcp_f32_e32 v70, v56
	v_rcp_f32_e32 v71, v57
	v_rcp_f32_e32 v204, v58
	v_pk_add_f32 v[54:55], v[14:15], 1.0 op_sel_hi:[1,0] neg_lo:[1,0] neg_hi:[1,0]
	v_pk_add_f32 v[56:57], v[48:49], 1.0 op_sel_hi:[1,0] neg_lo:[1,0] neg_hi:[1,0]
	v_pk_add_f32 v[62:63], v[50:51], 1.0 op_sel_hi:[1,0] neg_lo:[1,0] neg_hi:[1,0]
	v_pk_add_f32 v[64:65], v[52:53], 1.0 op_sel_hi:[1,0] neg_lo:[1,0] neg_hi:[1,0]
	v_pk_mul_f32 v[58:59], v[54:55], v[56:57]
	v_pk_add_f32 v[72:73], v[68:69], 1.0 op_sel_hi:[1,0] neg_lo:[1,0] neg_hi:[1,0]
	v_pk_add_f32 v[74:75], v[70:71], 1.0 op_sel_hi:[1,0] neg_lo:[1,0] neg_hi:[1,0]
	v_mul_f32_e32 v214, v58, v59
	v_pk_mul_f32 v[58:59], v[62:63], v[64:65]
	v_pk_add_f32 v[206:207], v[192:193], 1.0 op_sel_hi:[1,0] neg_lo:[1,0] neg_hi:[1,0]
	v_pk_add_f32 v[76:77], v[204:205], 1.0 op_sel_hi:[1,0] neg_lo:[1,0] neg_hi:[1,0]
	v_mul_f32_e32 v54, v58, v59
	v_pk_mul_f32 v[58:59], v[72:73], v[74:75]
	v_mov_b32_e32 v67, v54
	v_mul_f32_e32 v62, v58, v59
	v_pk_mul_f32 v[58:59], v[206:207], v[76:77]
	v_mov_b32_e32 v61, v62
	v_mul_f32_e32 v58, v58, v59
	v_mov_b32_e32 v59, v58
	v_mov_b32_e32 v215, v214
	v_permlane32_swap_b32_e32 v67, v54
	v_permlane32_swap_b32_e32 v61, v62
	v_permlane32_swap_b32_e32 v58, v59
	v_permlane32_swap_b32_e32 v214, v215
	s_nop 1
	v_mul_f32_e32 v58, v58, v59
	v_mul_f32_e32 v62, v62, v58
	v_mul_f32_e32 v61, v61, v62
	v_mul_f32_e32 v54, v54, v61
	v_mul_f32_e32 v66, v67, v54
	v_mul_f32_e32 v206, v215, v66
	v_cndmask_b32_e64 v60, v66, v206, s[4:5]
	v_cndmask_b32_e64 v72, 1.0, v59, s[4:5]
	v_mul_f32_e32 v59, v139, v60
	v_cndmask_b32_e64 v54, v61, v54, s[4:5]
	v_cndmask_b32_e64 v61, v58, v62, s[4:5]
	v_mul_f32_e32 v58, v57, v59
	v_mul_f32_e32 v57, v56, v58
	v_mul_f32_e32 v56, v55, v57
	v_mul_f32_e32 v55, v139, v54
	v_mul_f32_e32 v54, v65, v55
	v_pk_mul_f32 v[14:15], v[14:15], v[56:57]
	v_mul_f32_e32 v57, v64, v54
	v_mul_f32_e32 v79, v139, v61
	v_mul_f32_e32 v56, v63, v57
	v_mul_f32_e32 v78, v75, v79
	v_pk_mul_f32 v[48:49], v[48:49], v[58:59]
	v_pk_mul_f32 v[50:51], v[50:51], v[56:57]
	v_pk_mul_f32 v[52:53], v[52:53], v[54:55]
	v_cvt_pk_bf16_f32 v200, v14, v15
	v_mul_f32_e32 v15, v74, v78
	v_mul_f32_e32 v211, v139, v72
	s_waitcnt lgkmcnt(0)
	v_cvt_pk_bf16_f32 v201, v48, v49
	v_cvt_pk_bf16_f32 v202, v50, v51
	v_cvt_pk_bf16_f32 v203, v52, v53
	v_mul_f32_e32 v14, v73, v15
	v_mul_f32_e32 v210, v211, v77
	v_mfma_f32_32x32x16_bf16 v[48:63], v[244:247], v[200:203], v[32:47]
	v_mul_f32_e64 v14, v68, v14
	v_mul_f32_e64 v15, v69, v15
	v_mul_f32_e64 v208, v70, v78
	v_mul_f32_e64 v209, v71, v79
	v_mul_f32_e32 v213, v76, v210
	v_mul_f32_e32 v212, v207, v213
	v_pk_mul_f32 v[192:193], v[192:193], v[212:213]
	v_mfma_f32_32x32x16_bf16 v[64:79], v[196:199], v[200:203], v[16:31]
	v_cvt_pk_bf16_f32 v196, v14, v15
	v_mul_f32_e32 v14, v214, v206
	v_mul_f32_e32 v14, v139, v14
	v_mul_f32_e64 v200, v204, v210
	v_mul_f32_e64 v201, v205, v211
	v_cmp_gt_f32_e32 vcc, s21, v14
	v_cvt_pk_bf16_f32 v197, v208, v209
	v_cvt_pk_bf16_f32 v198, v192, v193
	v_cvt_pk_bf16_f32 v199, v200, v201
	s_cmp_eq_u64 vcc, exec
	s_cselect_b64 s[18:19], -1, 0
	v_mfma_f32_32x32x16_bf16 v[48:63], v[188:191], v[196:199], v[48:63]
	v_mfma_f32_32x32x16_bf16 v[64:79], v[184:187], v[196:199], v[64:79]
